# diff-attn stage loop: K/V fragment LDS addresses of the next stage computed before the stage barrier (no VALU at segment head)
# baseline (speedup 1.0000x reference)
; #define DF_WAITBAR(N) asm volatile("s_waitcnt vmcnt(" #N ") lgkmcnt(0)\n\ts_barrier" ::: "memory")
; DI void diff_unit(const Args& A, const bf16_t* QKV, bf16_t* ATT, unsigned char* lds, LAS unsigned char* lds3, int b, int head, int qb, int tid, int wid, int lane) {
;     const int r32 = lane & 31, hi = lane >> 5, comp = wid >> 2, wq = wid & 3;
;     const size_t rowbase = (size_t)b * SEQ;
;     const int q0 = qb * 128 + wq * 32;
;     const int qcol = 1536 + head * 128 + comp * 64;
;     bf16x8 qf[4];
; #pragma unroll
;     for (int c = 0; c < 4; ++c) qf[c] = *(const bf16x8*)(QKV + (rowbase + q0 + r32) * QKVW + qcol + 16 * c + 8 * hi);
;     f32x16 o[4];
; #pragma unroll
;     for (int t = 0; t < 4; ++t)
; #pragma unroll
;         for (int i = 0; i < 16; ++i) o[t][i] = 0.f;
;     float m = -INFINITY, l = 0.f;
;     const int nst = 2 * (qb + 1);
;     const unsigned ldsb = (unsigned)(uintptr_t)lds3;
;     const int kkey = 8 * wid + (lane >> 3), kch = (lane & 7) ^ ((kkey >> 1) & 7);
;     const int vi0 = 2 * wid, vi1 = 2 * wid + 1;
;     const bf16_t* sbase = QKV + rowbase * QKVW + head * 128;
;     const unsigned oK = (unsigned)((kkey * QKVW + 2048 + kch * 8) * 2);
;     const unsigned oV0 = (unsigned)(((16 * (vi0 & 3) + (lane >> 2)) * QKVW + 2560 + ((vi0 >> 2) * 4 + (lane & 3)) * 8) * 2);
;     const unsigned oV1 = (unsigned)(((16 * (vi1 & 3) + (lane >> 2)) * QKVW + 2560 + ((vi1 >> 2) * 4 + (lane & 3)) * 8) * 2);
;     const unsigned dK = (unsigned)__builtin_amdgcn_readfirstlane(wid * 1024);
;     const unsigned dV0 = (unsigned)__builtin_amdgcn_readfirstlane(DF_V + (vi0 >> 2) * 4096 + (vi0 & 3) * 1024), dV1 = (unsigned)__builtin_amdgcn_readfirstlane(DF_V + (vi1 >> 2) * 4096 + (vi1 & 3) * 1024);
;     ...
;     DF_DMA(0, 0); DF_DMA(1, 1);
;     asm volatile("" : "+v"(qf[0]), "+v"(qf[1]), "+v"(qf[2]), "+v"(qf[3]));
;     DF_WAITBAR(4);
;     const int vlane = (4 * hi + ((lane & 15) >> 2)) * 64 + ((lane >> 4) & 1) * 32 + (lane & 3) * 8;
;     const bool skew = false;
;     bf16x8 pp[4]; { const bf16x8 z8 = {0, 0, 0, 0, 0, 0, 0, 0}; pp[0] = z8; pp[1] = z8; pp[2] = z8; pp[3] = z8; } int pvo = vlane; bool have_prev = false;
;     for (int t = 0; t < nst; ++t) {
;         { const int tl = (t + 2 < nst) ? t + 2 : nst - 1; DF_DMA(tl, (t + 2) & 3); }
.LBB0_278:
	s_and_b32 s49, s7, 63
	s_ashr_i32 s6, s7, 8
	s_xor_b32 s24, s49, 0x7f
	s_bfe_u32 s22, s7, 0x20006
	s_ashr_i32 s7, s6, 31
	s_lshl_b32 s25, s24, 7
	s_lshl_b64 s[26:27], s[6:7], 14
	s_or_b32 s7, s25, s34
	v_or_b32_e32 v1, s7, v129
	s_lshl_b32 s48, s22, 7
	v_or_b32_e32 v154, s26, v1
	v_mad_u64_u32 v[2:3], s[8:9], v154, s43, v[140:141]
	s_add_u32 s28, s35, s48
	v_mad_i32_i24 v3, s27, v169, v3
	s_addc_u32 s29, s42, 0
	v_lshl_add_u64 v[2:3], s[28:29], 1, v[2:3]
	v_lshl_add_u64 v[2:3], v[2:3], 0, v[144:145]
	global_load_dwordx4 v[112:115], v[2:3], off offset:3168
	global_load_dwordx4 v[116:119], v[2:3], off offset:3136
	global_load_dwordx4 v[120:123], v[2:3], off offset:3104
	global_load_dwordx4 v[124:127], v[2:3], off offset:3072
	s_mul_hi_i32 s31, s6, 0x6000000
	s_mul_i32 s50, s6, 0x6000000
	s_lshl_b32 s6, s24, 1
	s_add_u32 s24, s12, s50
	v_add_u32_e32 v146, s25, v168
	s_addc_u32 s25, s13, s31
	s_lshl_b32 s22, s22, 8
	v_readfirstlane_b32 s30, v170
	s_add_u32 s24, s24, s22
	s_addc_u32 s25, s25, 0
	s_lshl_b32 s50, s30, 10
	s_mov_b32 s30, m0
	s_mov_b32 m0, s50
	s_nop 0
	global_load_lds_dwordx4 v156, s[24:25]
	s_mov_b32 m0, s30
	s_add_i32 s51, s50, 0x2000
	s_mov_b32 s30, m0
	s_mov_b32 m0, s51
	s_nop 0
	global_load_lds_dwordx4 v159, s[24:25]
	s_mov_b32 m0, s30
	v_readfirstlane_b32 s9, v171
	s_mov_b32 s31, m0
	s_mov_b32 m0, s9
	s_nop 0
	global_load_lds_dwordx4 v157, s[24:25]
	s_mov_b32 m0, s31
	v_readfirstlane_b32 s10, v172
	s_add_u32 s30, s24, 0x60000
	s_mov_b32 s58, m0
	s_mov_b32 m0, s10
	s_nop 0
	global_load_lds_dwordx4 v158, s[24:25]
	s_mov_b32 m0, s58
	s_addc_u32 s31, s25, 0
	s_add_i32 s54, s50, 0x8000
	s_mov_b32 s58, m0
	s_mov_b32 m0, s54
	s_nop 0
	global_load_lds_dwordx4 v156, s[30:31]
	s_mov_b32 m0, s58
	s_add_i32 s55, s50, 0xa000
	s_mov_b32 s54, m0
	s_mov_b32 m0, s55
	s_nop 0
	global_load_lds_dwordx4 v159, s[30:31]
	s_mov_b32 m0, s54
	s_add_i32 s56, s9, 0x8000
	s_mov_b32 s54, m0
	s_mov_b32 m0, s56
	s_nop 0
	global_load_lds_dwordx4 v157, s[30:31]
	s_mov_b32 m0, s54
	v_mov_b32_e32 v14, v0
	v_mov_b32_e32 v15, v0
	s_add_i32 s57, s10, 0x8000
	s_mov_b32 s54, m0
	s_mov_b32 m0, s57
	s_nop 0
	global_load_lds_dwordx4 v158, s[30:31]
	s_mov_b32 m0, s54
	v_mov_b32_e32 v1, v0
	v_mov_b32_e32 v2, v0
	v_mov_b32_e32 v3, v0
	v_mov_b32_e32 v4, v0
	v_mov_b32_e32 v5, v0
	v_mov_b32_e32 v6, v0
	v_mov_b32_e32 v7, v0
	v_mov_b32_e32 v8, v0
	v_mov_b32_e32 v9, v0
	v_mov_b32_e32 v10, v0
	v_mov_b32_e32 v11, v0
	v_mov_b32_e32 v12, v0
	v_mov_b32_e32 v13, v0
	v_mov_b64_e32 v[30:31], v[14:15]
	v_mov_b64_e32 v[46:47], v[14:15]
	v_mov_b64_e32 v[62:63], v[14:15]
	v_mov_b64_e32 v[78:79], v[14:15]
	s_mov_b32 s8, 63
	s_mov_b32 s11, 0
	v_mov_b32_e32 v143, 0
	v_mov_b32_e32 v147, 0xff800000
	v_mov_b64_e32 v[28:29], v[12:13]
	v_mov_b64_e32 v[26:27], v[10:11]
	v_mov_b64_e32 v[24:25], v[8:9]
	v_mov_b64_e32 v[22:23], v[6:7]
	v_mov_b64_e32 v[20:21], v[4:5]
	v_mov_b64_e32 v[18:19], v[2:3]
	v_mov_b64_e32 v[16:17], v[0:1]
	v_mov_b32_e32 v155, s27
	s_or_b32 s52, s6, 1
	s_or_b32 s53, s7, 31
	v_mov_b64_e32 v[44:45], v[12:13]
	v_mov_b64_e32 v[42:43], v[10:11]
	v_mov_b64_e32 v[40:41], v[8:9]
	v_mov_b64_e32 v[38:39], v[6:7]
	v_mov_b64_e32 v[36:37], v[4:5]
	v_mov_b64_e32 v[34:35], v[2:3]
	v_mov_b64_e32 v[32:33], v[0:1]
	v_mov_b64_e32 v[60:61], v[12:13]
	v_mov_b64_e32 v[58:59], v[10:11]
	v_mov_b64_e32 v[56:57], v[8:9]
	s_waitcnt vmcnt(0)
	s_waitcnt vmcnt(4) lgkmcnt(0)
	s_barrier
	v_mov_b64_e32 v[54:55], v[6:7]
	v_mov_b64_e32 v[52:53], v[4:5]
	v_mov_b64_e32 v[50:51], v[2:3]
	v_mov_b64_e32 v[48:49], v[0:1]
	s_mov_b32 s54, 0
	v_mov_b64_e32 v[76:77], v[12:13]
	v_mov_b64_e32 v[74:75], v[10:11]
	v_mov_b64_e32 v[72:73], v[8:9]
	v_mov_b64_e32 v[70:71], v[6:7]
	v_mov_b64_e32 v[68:69], v[4:5]
	v_mov_b64_e32 v[66:67], v[2:3]
	v_mov_b64_e32 v[64:65], v[0:1]
	s_mov_b32 s60, 0
	s_mov_b32 s61, 0
	s_mov_b32 s62, m0
	v_mov_b32_e32 v240, 0
	v_mov_b32_e32 v241, 0
	v_mov_b32_e32 v242, 0
	v_mov_b32_e32 v243, 0
	v_mov_b32_e32 v244, 0
	v_mov_b32_e32 v245, 0
	v_mov_b32_e32 v246, 0
	v_mov_b32_e32 v247, 0
	v_mov_b32_e32 v248, 0
	v_mov_b32_e32 v249, 0
	v_mov_b32_e32 v250, 0
	v_mov_b32_e32 v251, 0
	v_mov_b32_e32 v252, 0
	v_mov_b32_e32 v253, 0
	v_mov_b32_e32 v254, 0
	v_mov_b32_e32 v255, 0
	s_and_b32 s66, s11, 0x18000
	v_add_u32_e32 v2, s66, v160
	v_add_u32_e32 v3, v2, v161
	v_add_u32_e32 v4, v2, v162
	v_add_u32_e32 v5, v2, v163
	v_add_u32_e32 v2, v2, v164
	v_add_u32_e32 v6, s66, v165
	s_add_i32 s66, s54, 2
	s_cmp_lt_u32 s54, s6
	s_cselect_b32 s64, s66, s52
	s_lshl_b32 s65, s64, 6
	s_mul_i32 s64, s64, 0x60000
	s_mul_hi_u32 s65, s65, 0x1800
	s_add_u32 s64, s24, s64
	s_addc_u32 s65, s25, s65
	s_lshl_b32 s66, s66, 15
	s_and_b32 s66, s66, 0x18000
	s_add_i32 s67, s66, s50
	s_add_i32 s68, s66, s51
	s_add_i32 s69, s66, s9
	s_add_i32 s70, s66, s10
	s_and_b64 vcc, exec, s[20:21]
	s_cbranch_vccnz .Ldf1a_loop
; #define DF_VLD(VF, VOFF, H) do { _Pragma("unroll") for (int d2 = 0; d2 < 2; ++d2) { LAS unsigned char* vb_ = lds3 + (VOFF) + (2 * (H) + d2) * 4096; VF[2 * d2] = vfrag(vb_); VF[2 * d2 + 1] = vfrag(vb_ + 1024); } } while (0)
; #define DF_PVM(VF, P0, P1, H) do { _Pragma("unroll") for (int d2 = 0; d2 < 2; ++d2) { o[2 * (H) + d2] = mfma32(VF[2 * d2], P0, o[2 * (H) + d2]); o[2 * (H) + d2] = mfma32(VF[2 * d2 + 1], P1, o[2 * (H) + d2]); } } while (0)
; #define DF_DMA(t, bufi) do { const bf16_t* sb_ = sbase + (size_t)(64 * (t)) * QKVW; const unsigned base_ = (unsigned)__builtin_amdgcn_readfirstlane(ldsb + (bufi) * DF_STAGE); \
;         glds16s(sb_, oK, base_ + dK); glds16s(sb_, oK + 128u, base_ + DF_K2 + dK); glds16s(sb_, oV0, base_ + dV0); glds16s(sb_, oV1, base_ + dV1); } while (0)
; DI void diff_stage(const unsigned char* lds, LAS unsigned char* lds3, int buf, int t, int comp, int q0, int r32, int hi, int vlane, bool skew,
;                    const bf16x8 (&qf)[4], f32x16 (&o)[4], float& m, float& l, bf16x8 (&pp)[4], int& pvo, bool& have_prev) {
;     const int k0 = 64 * t;
;     if (k0 > q0 + 31) return;
;     const unsigned char* sb = lds + buf * DF_STAGE + comp * DF_K2 + r32 * 128; const int ke16 = (hi ^ ((r32 >> 1) & 7)) * 16;
;     bf16x8 vf[4];
;     if (skew && have_prev) {
; #pragma unroll
;         for (int sub = 0; sub < 2; ++sub) { DF_VLD(vf, pvo + sub * 2048, 0); DF_PVM(vf, pp[2 * sub], pp[2 * sub + 1], 0); DF_VLD(vf, pvo + sub * 2048, 1); DF_PVM(vf, pp[2 * sub], pp[2 * sub + 1], 1); }
;     }
;     f32x16 s0, s1;
; #pragma unroll
;     for (int i = 0; i < 16; ++i) { s0[i] = 0.f; s1[i] = 0.f; }
;     {
;         bf16x8 k0f[4], k1f[4];
; #pragma unroll
;         for (int c = 0; c < 4; ++c) { k0f[c] = *(const bf16x8*)(sb + ((32 * c) ^ ke16)); k1f[c] = *(const bf16x8*)(sb + 32 * 128 + ((32 * c) ^ ke16)); }
; DI void diff_unit(const Args& A, const bf16_t* QKV, bf16_t* ATT, unsigned char* lds, LAS unsigned char* lds3, int b, int head, int qb, int tid, int wid, int lane) {
;     ...
;         { const int tl = (t + 2 < nst) ? t + 2 : nst - 1; DF_DMA(tl, (t + 2) & 3); }
.Ldf1b_loop:
	s_sub_i32 s71, s8, 63
	s_cmp_gt_u32 s71, s53
	s_cbranch_scc1 .Ldf1b_skip
	s_and_b32 s55, s11, 0x18000
	ds_read_b128 v[208:211], v3
	ds_read_b128 v[212:215], v3 offset:4096
	ds_read_b128 v[216:219], v4
	ds_read_b128 v[220:223], v4 offset:4096
	ds_read_b128 v[224:227], v5
	ds_read_b128 v[228:231], v5 offset:4096
	ds_read_b128 v[232:235], v2
	ds_read_b128 v[236:239], v2 offset:4096
	s_mov_b32 m0, s67
	s_nop 0
	global_load_lds_dwordx4 v156, s[64:65]
	s_mov_b32 m0, s68
	s_nop 0
	global_load_lds_dwordx4 v159, s[64:65]
	s_mov_b32 m0, s69
	s_nop 0
	global_load_lds_dwordx4 v157, s[64:65]
	s_mov_b32 m0, s70
	s_nop 0
	global_load_lds_dwordx4 v158, s[64:65]
	s_cmp_eq_u32 s60, 0
	s_cbranch_scc1 .Ldf1bs_noresc
	v_pk_mul_f32 v[78:79], v[78:79], v[206:207] op_sel_hi:[1,0]
	v_pk_mul_f32 v[76:77], v[76:77], v[206:207] op_sel_hi:[1,0]
	v_pk_mul_f32 v[74:75], v[74:75], v[206:207] op_sel_hi:[1,0]
	v_pk_mul_f32 v[72:73], v[72:73], v[206:207] op_sel_hi:[1,0]
	v_pk_mul_f32 v[70:71], v[70:71], v[206:207] op_sel_hi:[1,0]
	v_pk_mul_f32 v[68:69], v[68:69], v[206:207] op_sel_hi:[1,0]
	v_pk_mul_f32 v[66:67], v[66:67], v[206:207] op_sel_hi:[1,0]
	v_pk_mul_f32 v[64:65], v[64:65], v[206:207] op_sel_hi:[1,0]
	v_pk_mul_f32 v[62:63], v[62:63], v[206:207] op_sel_hi:[1,0]
	v_pk_mul_f32 v[60:61], v[60:61], v[206:207] op_sel_hi:[1,0]
	v_pk_mul_f32 v[58:59], v[58:59], v[206:207] op_sel_hi:[1,0]
	v_pk_mul_f32 v[56:57], v[56:57], v[206:207] op_sel_hi:[1,0]
	v_pk_mul_f32 v[54:55], v[54:55], v[206:207] op_sel_hi:[1,0]
	v_pk_mul_f32 v[52:53], v[52:53], v[206:207] op_sel_hi:[1,0]
	v_pk_mul_f32 v[50:51], v[50:51], v[206:207] op_sel_hi:[1,0]
	v_pk_mul_f32 v[48:49], v[48:49], v[206:207] op_sel_hi:[1,0]
	v_pk_mul_f32 v[46:47], v[46:47], v[206:207] op_sel_hi:[1,0]
	v_pk_mul_f32 v[44:45], v[44:45], v[206:207] op_sel_hi:[1,0]
	v_pk_mul_f32 v[42:43], v[42:43], v[206:207] op_sel_hi:[1,0]
	v_pk_mul_f32 v[40:41], v[40:41], v[206:207] op_sel_hi:[1,0]
	v_pk_mul_f32 v[38:39], v[38:39], v[206:207] op_sel_hi:[1,0]
	v_pk_mul_f32 v[36:37], v[36:37], v[206:207] op_sel_hi:[1,0]
	v_pk_mul_f32 v[34:35], v[34:35], v[206:207] op_sel_hi:[1,0]
	v_pk_mul_f32 v[32:33], v[32:33], v[206:207] op_sel_hi:[1,0]
	v_pk_mul_f32 v[30:31], v[30:31], v[206:207] op_sel_hi:[1,0]
	v_pk_mul_f32 v[28:29], v[28:29], v[206:207] op_sel_hi:[1,0]
	v_pk_mul_f32 v[26:27], v[26:27], v[206:207] op_sel_hi:[1,0]
	v_pk_mul_f32 v[24:25], v[24:25], v[206:207] op_sel_hi:[1,0]
	v_pk_mul_f32 v[22:23], v[22:23], v[206:207] op_sel_hi:[1,0]
	v_pk_mul_f32 v[20:21], v[20:21], v[206:207] op_sel_hi:[1,0]
	v_pk_mul_f32 v[18:19], v[18:19], v[206:207] op_sel_hi:[1,0]
	v_pk_mul_f32 v[16:17], v[16:17], v[206:207] op_sel_hi:[1,0]
	s_mov_b32 s60, 0

; #define DF_DMA(t, bufi) do { const bf16_t* sb_ = sbase + (size_t)(64 * (t)) * QKVW; const unsigned base_ = (unsigned)__builtin_amdgcn_readfirstlane(ldsb + (bufi) * DF_STAGE); \
;         glds16s(sb_, oK, base_ + dK); glds16s(sb_, oK + 128u, base_ + DF_K2 + dK); glds16s(sb_, oV0, base_ + dV0); glds16s(sb_, oV1, base_ + dV1); } while (0)
; #define DF_WAITBAR(N) asm volatile("s_waitcnt vmcnt(" #N ") lgkmcnt(0)\n\ts_barrier" ::: "memory")
; DI void diff_unit(const Args& A, const bf16_t* QKV, bf16_t* ATT, unsigned char* lds, LAS unsigned char* lds3, int b, int head, int qb, int tid, int wid, int lane) {
;     ...
;     for (int t = 0; t < nst; ++t) {
;         { const int tl = (t + 2 < nst) ? t + 2 : nst - 1; DF_DMA(tl, (t + 2) & 3); }
;         diff_stage(lds, lds3, t & 3, t, comp, q0, r32, hi, vlane, skew, qf, o, m, l, pp, pvo, have_prev);
;         DF_WAITBAR(4);
;     }
.Ldf1b_bar:
	s_waitcnt vmcnt(4) lgkmcnt(0)
	s_add_i32 s11, s11, 0x8000
	s_and_b32 s66, s11, 0x18000
	v_add_u32_e32 v2, s66, v160
	v_add_u32_e32 v3, v2, v161
	v_add_u32_e32 v4, v2, v162
	v_add_u32_e32 v5, v2, v163
	v_add_u32_e32 v2, v2, v164
	s_add_i32 s56, s11, 0x18000
	s_cmp_eq_u32 s61, 0
	s_cselect_b32 s56, s11, s56
	s_and_b32 s56, s56, 0x18000
	v_add_u32_e32 v6, s56, v165
	s_add_i32 s8, s8, 64
	v_subrev_u32_e32 v146, 64, v146
	s_add_i32 s55, s54, 1
	s_add_i32 s66, s55, 2
	s_cmp_lt_u32 s55, s6
	s_cselect_b32 s64, s66, s52
	s_lshl_b32 s65, s64, 6
	s_mul_i32 s64, s64, 0x60000
	s_mul_hi_u32 s65, s65, 0x1800
	s_add_u32 s64, s24, s64
	s_addc_u32 s65, s25, s65
	s_lshl_b32 s66, s66, 15
	s_and_b32 s66, s66, 0x18000
	s_add_i32 s67, s66, s50
	s_add_i32 s68, s66, s51
	s_add_i32 s69, s66, s9
	s_add_i32 s70, s66, s10
	s_cmp_eq_u32 s54, s52
	s_barrier
	s_cbranch_scc1 .Ldf1b_exit
	s_mov_b32 s54, s55
	s_branch .Ldf1b_loop

; DI f32x16 mfma32(bf16x8 a, bf16x8 b, f32x16 c) { return __builtin_amdgcn_mfma_f32_32x32x16_bf16(a, b, c, 0, 0, 0); }
; #define DF_VLD(VF, VOFF, H) do { _Pragma("unroll") for (int d2 = 0; d2 < 2; ++d2) { LAS unsigned char* vb_ = lds3 + (VOFF) + (2 * (H) + d2) * 4096; VF[2 * d2] = vfrag(vb_); VF[2 * d2 + 1] = vfrag(vb_ + 1024); } } while (0)
; #define DF_PVM(VF, P0, P1, H) do { _Pragma("unroll") for (int d2 = 0; d2 < 2; ++d2) { o[2 * (H) + d2] = mfma32(VF[2 * d2], P0, o[2 * (H) + d2]); o[2 * (H) + d2] = mfma32(VF[2 * d2 + 1], P1, o[2 * (H) + d2]); } } while (0)
; DI void diff_stage(const unsigned char* lds, LAS unsigned char* lds3, int buf, int t, int comp, int q0, int r32, int hi, int vlane, bool skew,
;                    const bf16x8 (&qf)[4], f32x16 (&o)[4], float& m, float& l, bf16x8 (&pp)[4], int& pvo, bool& have_prev) {
;     const int k0 = 64 * t;
;     if (k0 > q0 + 31) return;
;     const unsigned char* sb = lds + buf * DF_STAGE + comp * DF_K2 + r32 * 128; const int ke16 = (hi ^ ((r32 >> 1) & 7)) * 16;
;     bf16x8 vf[4];
;     if (skew && have_prev) {
; #pragma unroll
;         for (int sub = 0; sub < 2; ++sub) { DF_VLD(vf, pvo + sub * 2048, 0); DF_PVM(vf, pp[2 * sub], pp[2 * sub + 1], 0); DF_VLD(vf, pvo + sub * 2048, 1); DF_PVM(vf, pp[2 * sub], pp[2 * sub + 1], 1); }
;     }
;     f32x16 s0, s1;
; #pragma unroll
;     for (int i = 0; i < 16; ++i) { s0[i] = 0.f; s1[i] = 0.f; }
;     {
;         bf16x8 k0f[4], k1f[4];
; #pragma unroll
;         for (int c = 0; c < 4; ++c) { k0f[c] = *(const bf16x8*)(sb + ((32 * c) ^ ke16)); k1f[c] = *(const bf16x8*)(sb + 32 * 128 + ((32 * c) ^ ke16)); }
; #pragma unroll
;         for (int c = 0; c < 4; ++c) { s0 = mfma32(k0f[c], qf[c], s0); s1 = mfma32(k1f[c], qf[c], s1); }
;     }
;     if (k0 + 63 > q0) {
;         const int dq = q0 + r32 - k0 - 4 * hi;
; #pragma unroll
;         for (int i = 0; i < 16; ++i) { const int ci = (i & 3) + 8 * (i >> 2); s0[i] = (ci > dq) ? -INFINITY : s0[i]; s1[i] = (ci + 32 > dq) ? -INFINITY : s1[i]; }
;     }
.Ldf1a_loop:
	s_sub_i32 s71, s8, 63
	s_cmp_gt_u32 s71, s53
	s_cbranch_scc1 .Ldf1a_skip
	s_and_b32 s55, s11, 0x18000
	ds_read_b128 v[208:211], v3
	ds_read_b128 v[212:215], v3 offset:4096
	ds_read_b128 v[216:219], v4
	ds_read_b128 v[220:223], v4 offset:4096
	ds_read_b128 v[224:227], v5
	ds_read_b128 v[228:231], v5 offset:4096
	ds_read_b128 v[232:235], v2
	ds_read_b128 v[236:239], v2 offset:4096
	s_mov_b32 m0, s67
	s_nop 0
	global_load_lds_dwordx4 v156, s[64:65]
	s_mov_b32 m0, s68
	s_nop 0
	global_load_lds_dwordx4 v159, s[64:65]
	s_mov_b32 m0, s69
	s_nop 0
	global_load_lds_dwordx4 v157, s[64:65]
	s_mov_b32 m0, s70
	s_nop 0
	global_load_lds_dwordx4 v158, s[64:65]
	s_waitcnt lgkmcnt(7)
	v_mfma_f32_32x32x16_bf16 v[96:111], v[208:211], v[124:127], 0
	s_waitcnt lgkmcnt(6)
	v_mfma_f32_32x32x16_bf16 v[80:95], v[212:215], v[124:127], 0
	s_waitcnt lgkmcnt(5)
	v_mfma_f32_32x32x16_bf16 v[96:111], v[216:219], v[120:123], v[96:111]
	s_waitcnt lgkmcnt(4)
	v_mfma_f32_32x32x16_bf16 v[80:95], v[220:223], v[120:123], v[80:95]
	s_waitcnt lgkmcnt(3)
	v_mfma_f32_32x32x16_bf16 v[96:111], v[224:227], v[116:119], v[96:111]
	s_waitcnt lgkmcnt(2)
	v_mfma_f32_32x32x16_bf16 v[80:95], v[228:231], v[116:119], v[80:95]
	s_waitcnt lgkmcnt(1)
	v_mfma_f32_32x32x16_bf16 v[96:111], v[232:235], v[112:115], v[96:111]
	s_waitcnt lgkmcnt(0)
	v_mfma_f32_32x32x16_bf16 v[80:95], v[236:239], v[112:115], v[80:95]
	ds_read_b64_tr_b16 v[208:209], v6 offset:16384
	ds_read_b64_tr_b16 v[210:211], v6 offset:16896
	ds_read_b64_tr_b16 v[212:213], v6 offset:17408
	ds_read_b64_tr_b16 v[214:215], v6 offset:17920
	ds_read_b64_tr_b16 v[216:217], v6 offset:20480
	ds_read_b64_tr_b16 v[218:219], v6 offset:20992
	ds_read_b64_tr_b16 v[220:221], v6 offset:21504
	ds_read_b64_tr_b16 v[222:223], v6 offset:22016
	ds_read_b64_tr_b16 v[224:225], v6 offset:24576
	ds_read_b64_tr_b16 v[226:227], v6 offset:25088
	ds_read_b64_tr_b16 v[228:229], v6 offset:25600
	ds_read_b64_tr_b16 v[230:231], v6 offset:26112
	s_cmp_le_u32 s8, s7
	s_cbranch_scc1 .Ldf1a_nodiag
	s_nop 7
	v_cmp_lt_i32_e32 vcc, -1, v146
	s_nop 1
	v_cndmask_b32_e32 v96, v176, v96, vcc
	v_cmp_lt_i32_e32 vcc, 31, v146
	s_nop 1
	v_cndmask_b32_e32 v80, v176, v80, vcc
	v_cmp_lt_i32_e32 vcc, 0, v146
	s_nop 1
	v_cndmask_b32_e32 v97, v176, v97, vcc
	v_cmp_lt_i32_e32 vcc, 32, v146
	s_nop 1
	v_cndmask_b32_e32 v81, v176, v81, vcc
	v_cmp_lt_i32_e32 vcc, 1, v146
	s_nop 1
	v_cndmask_b32_e32 v98, v176, v98, vcc
	v_cmp_lt_i32_e32 vcc, 33, v146
	s_nop 1
	v_cndmask_b32_e32 v82, v176, v82, vcc
	v_cmp_lt_i32_e32 vcc, 2, v146
	s_nop 1
	v_cndmask_b32_e32 v99, v176, v99, vcc
	v_cmp_lt_i32_e32 vcc, 34, v146
	s_nop 1
	v_cndmask_b32_e32 v83, v176, v83, vcc
	v_cmp_lt_i32_e32 vcc, 7, v146
	s_nop 1
	v_cndmask_b32_e32 v100, v176, v100, vcc
	v_cmp_lt_i32_e32 vcc, 39, v146
	s_nop 1
	v_cndmask_b32_e32 v84, v176, v84, vcc
	v_cmp_lt_i32_e32 vcc, 8, v146
	s_nop 1
	v_cndmask_b32_e32 v101, v176, v101, vcc
	v_cmp_lt_i32_e32 vcc, 40, v146
	s_nop 1
	v_cndmask_b32_e32 v85, v176, v85, vcc
	v_cmp_lt_i32_e32 vcc, 9, v146
	s_nop 1
	v_cndmask_b32_e32 v102, v176, v102, vcc
	v_cmp_lt_i32_e32 vcc, 41, v146
	s_nop 1
	v_cndmask_b32_e32 v86, v176, v86, vcc
	v_cmp_lt_i32_e32 vcc, 10, v146
	s_nop 1
	v_cndmask_b32_e32 v103, v176, v103, vcc
	v_cmp_lt_i32_e32 vcc, 42, v146
	s_nop 1
	v_cndmask_b32_e32 v87, v176, v87, vcc
	v_cmp_lt_i32_e32 vcc, 15, v146
	s_nop 1
	v_cndmask_b32_e32 v104, v176, v104, vcc
	v_cmp_lt_i32_e32 vcc, 47, v146
	s_nop 1
	v_cndmask_b32_e32 v88, v176, v88, vcc
	v_cmp_lt_i32_e32 vcc, 16, v146
	s_nop 1
	v_cndmask_b32_e32 v105, v176, v105, vcc
	v_cmp_lt_i32_e32 vcc, 48, v146
	s_nop 1
	v_cndmask_b32_e32 v89, v176, v89, vcc
	v_cmp_lt_i32_e32 vcc, 17, v146
	s_nop 1
	v_cndmask_b32_e32 v106, v176, v106, vcc
	v_cmp_lt_i32_e32 vcc, 49, v146
	s_nop 1
	v_cndmask_b32_e32 v90, v176, v90, vcc
	v_cmp_lt_i32_e32 vcc, 18, v146
	s_nop 1
	v_cndmask_b32_e32 v107, v176, v107, vcc
	v_cmp_lt_i32_e32 vcc, 50, v146
	s_nop 1
	v_cndmask_b32_e32 v91, v176, v91, vcc
	v_cmp_lt_i32_e32 vcc, 23, v146
	s_nop 1
	v_cndmask_b32_e32 v108, v176, v108, vcc
	v_cmp_lt_i32_e32 vcc, 55, v146
	s_nop 1
	v_cndmask_b32_e32 v92, v176, v92, vcc
	v_cmp_lt_i32_e32 vcc, 24, v146
	s_nop 1
	v_cndmask_b32_e32 v109, v176, v109, vcc
	v_cmp_lt_i32_e32 vcc, 56, v146
	s_nop 1
	v_cndmask_b32_e32 v93, v176, v93, vcc
	v_cmp_lt_i32_e32 vcc, 25, v146
	s_nop 1
	v_cndmask_b32_e32 v110, v176, v110, vcc
	v_cmp_lt_i32_e32 vcc, 57, v146
	s_nop 1
	v_cndmask_b32_e32 v94, v176, v94, vcc
	v_cmp_lt_i32_e32 vcc, 26, v146
	s_nop 1
	v_cndmask_b32_e32 v111, v176, v111, vcc
	v_cmp_lt_i32_e32 vcc, 58, v146
	s_nop 1
	v_cndmask_b32_e32 v95, v176, v95, vcc

; #define DF_DMA(t, bufi) do { const bf16_t* sb_ = sbase + (size_t)(64 * (t)) * QKVW; const unsigned base_ = (unsigned)__builtin_amdgcn_readfirstlane(ldsb + (bufi) * DF_STAGE); \
;         glds16s(sb_, oK, base_ + dK); glds16s(sb_, oK + 128u, base_ + DF_K2 + dK); glds16s(sb_, oV0, base_ + dV0); glds16s(sb_, oV1, base_ + dV1); } while (0)
; #define DF_WAITBAR(N) asm volatile("s_waitcnt vmcnt(" #N ") lgkmcnt(0)\n\ts_barrier" ::: "memory")
; DI void diff_unit(const Args& A, const bf16_t* QKV, bf16_t* ATT, unsigned char* lds, LAS unsigned char* lds3, int b, int head, int qb, int tid, int wid, int lane) {
;     ...
;     for (int t = 0; t < nst; ++t) {
;         { const int tl = (t + 2 < nst) ? t + 2 : nst - 1; DF_DMA(tl, (t + 2) & 3); }
;         diff_stage(lds, lds3, t & 3, t, comp, q0, r32, hi, vlane, skew, qf, o, m, l, pp, pvo, have_prev);
;         DF_WAITBAR(4);
;     }
.Ldf1a_bar:
	s_waitcnt vmcnt(4) lgkmcnt(0)
	s_add_i32 s11, s11, 0x8000
	s_and_b32 s66, s11, 0x18000
	v_add_u32_e32 v2, s66, v160
	v_add_u32_e32 v3, v2, v161
	v_add_u32_e32 v4, v2, v162
	v_add_u32_e32 v5, v2, v163
	v_add_u32_e32 v2, v2, v164
	v_add_u32_e32 v6, s66, v165
	s_add_i32 s8, s8, 64
	v_subrev_u32_e32 v146, 64, v146
	s_add_i32 s55, s54, 1
	s_add_i32 s66, s55, 2
	s_cmp_lt_u32 s55, s6
	s_cselect_b32 s64, s66, s52
	s_lshl_b32 s65, s64, 6
	s_mul_i32 s64, s64, 0x60000
	s_mul_hi_u32 s65, s65, 0x1800
	s_add_u32 s64, s24, s64
	s_addc_u32 s65, s25, s65
	s_lshl_b32 s66, s66, 15
	s_and_b32 s66, s66, 0x18000
	s_add_i32 s67, s66, s50
	s_add_i32 s68, s66, s51
	s_add_i32 s69, s66, s9
	s_add_i32 s70, s66, s10
	s_cmp_eq_u32 s54, s52
	s_barrier
	s_cbranch_scc1 .Ldf1a_exit
	s_mov_b32 s54, s55
	s_branch .Ldf1a_loop

; #define DF_WAITBAR(N) asm volatile("s_waitcnt vmcnt(" #N ") lgkmcnt(0)\n\ts_barrier" ::: "memory")
; DI void diff_unit(const Args& A, const bf16_t* QKV, bf16_t* ATT, unsigned char* lds, LAS unsigned char* lds3, int b, int head, int qb, int tid, int wid, int lane) {
;     const int r32 = lane & 31, hi = lane >> 5, comp = wid >> 2, wq = wid & 3;
;     const size_t rowbase = (size_t)b * SEQ;
;     const int q0 = qb * 128 + wq * 32;
;     const int qcol = 1536 + head * 128 + comp * 64;
;     bf16x8 qf[4];
; #pragma unroll
;     for (int c = 0; c < 4; ++c) qf[c] = *(const bf16x8*)(QKV + (rowbase + q0 + r32) * QKVW + qcol + 16 * c + 8 * hi);
;     f32x16 o[4];
; #pragma unroll
;     for (int t = 0; t < 4; ++t)
; #pragma unroll
;         for (int i = 0; i < 16; ++i) o[t][i] = 0.f;
;     float m = -INFINITY, l = 0.f;
;     const int nst = 2 * (qb + 1);
;     const unsigned ldsb = (unsigned)(uintptr_t)lds3;
;     const int kkey = 8 * wid + (lane >> 3), kch = (lane & 7) ^ ((kkey >> 1) & 7);
;     const int vi0 = 2 * wid, vi1 = 2 * wid + 1;
;     const bf16_t* sbase = QKV + rowbase * QKVW + head * 128;
;     const unsigned oK = (unsigned)((kkey * QKVW + 2048 + kch * 8) * 2);
;     const unsigned oV0 = (unsigned)(((16 * (vi0 & 3) + (lane >> 2)) * QKVW + 2560 + ((vi0 >> 2) * 4 + (lane & 3)) * 8) * 2);
;     const unsigned oV1 = (unsigned)(((16 * (vi1 & 3) + (lane >> 2)) * QKVW + 2560 + ((vi1 >> 2) * 4 + (lane & 3)) * 8) * 2);
;     const unsigned dK = (unsigned)__builtin_amdgcn_readfirstlane(wid * 1024);
;     const unsigned dV0 = (unsigned)__builtin_amdgcn_readfirstlane(DF_V + (vi0 >> 2) * 4096 + (vi0 & 3) * 1024), dV1 = (unsigned)__builtin_amdgcn_readfirstlane(DF_V + (vi1 >> 2) * 4096 + (vi1 & 3) * 1024);
;     ...
;     DF_DMA(0, 0); DF_DMA(1, 1);
;     asm volatile("" : "+v"(qf[0]), "+v"(qf[1]), "+v"(qf[2]), "+v"(qf[3]));
;     DF_WAITBAR(4);
;     const int vlane = (4 * hi + ((lane & 15) >> 2)) * 64 + ((lane >> 4) & 1) * 32 + (lane & 3) * 8;
;     const bool skew = false;
;     bf16x8 pp[4]; { const bf16x8 z8 = {0, 0, 0, 0, 0, 0, 0, 0}; pp[0] = z8; pp[1] = z8; pp[2] = z8; pp[3] = z8; } int pvo = vlane; bool have_prev = false;
;     for (int t = 0; t < nst; ++t) {
;         { const int tl = (t + 2 < nst) ? t + 2 : nst - 1; DF_DMA(tl, (t + 2) & 3); }
.LBB0_291:
	s_lshl_b32 s52, s49, 7
	s_or_b32 s10, s52, s34
	v_or_b32_e32 v1, s10, v129
	v_or_b32_e32 v154, s26, v1
	v_mov_b64_e32 v[2:3], s[12:13]
	v_mad_u64_u32 v[2:3], s[50:51], v154, s43, v[2:3]
	v_mad_i32_i24 v3, s27, v169, v3
	v_lshl_add_u64 v[2:3], s[28:29], 1, v[2:3]
	v_mov_b32_e32 v143, v0
	v_lshl_add_u64 v[2:3], v[2:3], 0, v[142:143]
	s_barrier
	global_load_dwordx4 v[112:115], v[2:3], off offset:3168
	global_load_dwordx4 v[116:119], v[2:3], off offset:3136
	global_load_dwordx4 v[120:123], v[2:3], off offset:3104
	global_load_dwordx4 v[124:127], v[2:3], off offset:3072
	s_lshl_b32 s22, s33, 10
	v_add_u32_e32 v183, s52, v168
	s_mov_b32 s52, m0
	s_mov_b32 m0, s22
	s_nop 0
	global_load_lds_dwordx4 v156, s[24:25]
	s_mov_b32 m0, s52
	s_add_i32 s28, s22, 0x2000
	s_mov_b32 s52, m0
	s_mov_b32 m0, s28
	s_nop 0
	global_load_lds_dwordx4 v159, s[24:25]
	s_mov_b32 m0, s52
	s_add_i32 s53, s22, 0x8000
	s_mov_b32 s52, m0
	s_mov_b32 m0, s36
	s_nop 0
	global_load_lds_dwordx4 v157, s[24:25]
	s_mov_b32 m0, s52
	s_add_i32 s54, s22, 0xa000
	s_mov_b32 s52, m0
	s_mov_b32 m0, s37
	s_nop 0
	global_load_lds_dwordx4 v158, s[24:25]
	s_mov_b32 m0, s52
	s_add_i32 s50, s36, 0x8000
	s_mov_b32 s52, m0
	s_mov_b32 m0, s53
	s_nop 0
	global_load_lds_dwordx4 v156, s[30:31]
	s_mov_b32 m0, s52
	s_add_i32 s51, s37, 0x8000
	s_mov_b32 s52, m0
	s_mov_b32 m0, s54
	s_nop 0
	global_load_lds_dwordx4 v159, s[30:31]
	s_mov_b32 m0, s52
	v_mov_b32_e32 v14, v0
	s_mov_b32 s52, m0
	s_mov_b32 m0, s50
	s_nop 0
	global_load_lds_dwordx4 v157, s[30:31]
	s_mov_b32 m0, s52
	v_mov_b32_e32 v15, v0
	s_mov_b32 s50, m0
	s_mov_b32 m0, s51
	s_nop 0
	global_load_lds_dwordx4 v158, s[30:31]
	s_mov_b32 m0, s50
	s_lshl_b32 s11, s49, 1
	v_mov_b32_e32 v1, v0
	v_mov_b32_e32 v2, v0
	v_mov_b32_e32 v3, v0
	v_mov_b32_e32 v4, v0
	v_mov_b32_e32 v5, v0
	v_mov_b32_e32 v6, v0
	v_mov_b32_e32 v7, v0
	v_mov_b32_e32 v8, v0
	v_mov_b32_e32 v9, v0
	v_mov_b32_e32 v10, v0
	v_mov_b32_e32 v11, v0
	v_mov_b32_e32 v12, v0
	v_mov_b32_e32 v13, v0
	v_mov_b64_e32 v[30:31], v[14:15]
	v_mov_b64_e32 v[46:47], v[14:15]
	v_mov_b64_e32 v[62:63], v[14:15]
	v_mov_b64_e32 v[78:79], v[14:15]
	v_mov_b32_e32 v155, s27
	s_mov_b32 s26, 0
	v_mov_b32_e32 v143, 0
	v_mov_b32_e32 v185, 0xff800000
	s_mov_b32 s27, 63
	s_or_b32 s29, s11, 1
	v_mov_b64_e32 v[28:29], v[12:13]
	v_mov_b64_e32 v[26:27], v[10:11]
	v_mov_b64_e32 v[24:25], v[8:9]
	v_mov_b64_e32 v[22:23], v[6:7]
	v_mov_b64_e32 v[20:21], v[4:5]
	v_mov_b64_e32 v[18:19], v[2:3]
	v_mov_b64_e32 v[16:17], v[0:1]
	s_or_b32 s49, s10, 31
	v_mov_b64_e32 v[44:45], v[12:13]
	v_mov_b64_e32 v[42:43], v[10:11]
	v_mov_b64_e32 v[40:41], v[8:9]
	v_mov_b64_e32 v[38:39], v[6:7]
	v_mov_b64_e32 v[36:37], v[4:5]
	v_mov_b64_e32 v[34:35], v[2:3]
	v_mov_b64_e32 v[32:33], v[0:1]
	v_mov_b64_e32 v[60:61], v[12:13]
	v_mov_b64_e32 v[58:59], v[10:11]
	v_mov_b64_e32 v[56:57], v[8:9]
	v_mov_b64_e32 v[54:55], v[6:7]
	v_mov_b64_e32 v[52:53], v[4:5]
	v_mov_b64_e32 v[50:51], v[2:3]
	v_mov_b64_e32 v[48:49], v[0:1]
	s_mov_b32 s30, 0
	v_mov_b64_e32 v[76:77], v[12:13]
	v_mov_b64_e32 v[74:75], v[10:11]
	v_mov_b64_e32 v[72:73], v[8:9]
	v_mov_b64_e32 v[70:71], v[6:7]
	v_mov_b64_e32 v[68:69], v[4:5]
	v_mov_b64_e32 v[66:67], v[2:3]
	v_mov_b64_e32 v[64:65], v[0:1]
	s_waitcnt vmcnt(0)
	s_waitcnt vmcnt(4) lgkmcnt(0)
	s_barrier
	s_mov_b32 s60, 0
	s_mov_b32 s61, 0
	s_mov_b32 s62, m0
	v_mov_b32_e32 v240, 0
	v_mov_b32_e32 v241, 0
	v_mov_b32_e32 v242, 0
	v_mov_b32_e32 v243, 0
	v_mov_b32_e32 v244, 0
	v_mov_b32_e32 v245, 0
	v_mov_b32_e32 v246, 0
	v_mov_b32_e32 v247, 0
	v_mov_b32_e32 v248, 0
	v_mov_b32_e32 v249, 0
	v_mov_b32_e32 v250, 0
	v_mov_b32_e32 v251, 0
	v_mov_b32_e32 v252, 0
	v_mov_b32_e32 v253, 0
	v_mov_b32_e32 v254, 0
	v_mov_b32_e32 v255, 0
	s_and_b32 s66, s26, 0x18000
	v_add_u32_e32 v2, s66, v160
	v_add_u32_e32 v3, v2, v161
	v_add_u32_e32 v4, v2, v162
	v_add_u32_e32 v5, v2, v163
	v_add_u32_e32 v2, v2, v164
	v_add_u32_e32 v6, s66, v165
	s_add_i32 s66, s30, 2
	s_cmp_lt_u32 s30, s11
	s_cselect_b32 s64, s66, s29
	s_lshl_b32 s65, s64, 6
	s_mul_i32 s64, s64, 0x60000
	s_mul_hi_u32 s65, s65, 0x1800
	s_add_u32 s64, s24, s64
	s_addc_u32 s65, s25, s65
	s_lshl_b32 s66, s66, 15
	s_and_b32 s66, s66, 0x18000
	s_add_i32 s67, s66, s22
	s_add_i32 s68, s66, s28
	s_add_i32 s69, s66, s36
	s_add_i32 s70, s66, s37
	s_and_b64 vcc, exec, s[20:21]
	s_cbranch_vccnz .Ldf2a_loop
.Ldf2b_loop:
	s_sub_i32 s71, s27, 63
	s_cmp_gt_u32 s71, s49
	s_cbranch_scc1 .Ldf2b_skip
	s_and_b32 s31, s26, 0x18000
	ds_read_b128 v[208:211], v3
	ds_read_b128 v[212:215], v3 offset:4096
	ds_read_b128 v[216:219], v4
	ds_read_b128 v[220:223], v4 offset:4096
	ds_read_b128 v[224:227], v5
	ds_read_b128 v[228:231], v5 offset:4096
	ds_read_b128 v[232:235], v2
	ds_read_b128 v[236:239], v2 offset:4096
	s_mov_b32 m0, s67
	s_nop 0
	global_load_lds_dwordx4 v156, s[64:65]
	s_mov_b32 m0, s68
	s_nop 0
	global_load_lds_dwordx4 v159, s[64:65]
	s_mov_b32 m0, s69
	s_nop 0
	global_load_lds_dwordx4 v157, s[64:65]
	s_mov_b32 m0, s70
	s_nop 0
	global_load_lds_dwordx4 v158, s[64:65]
	s_cmp_eq_u32 s60, 0
	s_cbranch_scc1 .Ldf2bs_noresc
	v_pk_mul_f32 v[78:79], v[78:79], v[206:207] op_sel_hi:[1,0]
	v_pk_mul_f32 v[76:77], v[76:77], v[206:207] op_sel_hi:[1,0]
	v_pk_mul_f32 v[74:75], v[74:75], v[206:207] op_sel_hi:[1,0]
	v_pk_mul_f32 v[72:73], v[72:73], v[206:207] op_sel_hi:[1,0]
	v_pk_mul_f32 v[70:71], v[70:71], v[206:207] op_sel_hi:[1,0]
	v_pk_mul_f32 v[68:69], v[68:69], v[206:207] op_sel_hi:[1,0]
	v_pk_mul_f32 v[66:67], v[66:67], v[206:207] op_sel_hi:[1,0]
	v_pk_mul_f32 v[64:65], v[64:65], v[206:207] op_sel_hi:[1,0]
	v_pk_mul_f32 v[62:63], v[62:63], v[206:207] op_sel_hi:[1,0]
	v_pk_mul_f32 v[60:61], v[60:61], v[206:207] op_sel_hi:[1,0]
	v_pk_mul_f32 v[58:59], v[58:59], v[206:207] op_sel_hi:[1,0]
	v_pk_mul_f32 v[56:57], v[56:57], v[206:207] op_sel_hi:[1,0]
	v_pk_mul_f32 v[54:55], v[54:55], v[206:207] op_sel_hi:[1,0]
	v_pk_mul_f32 v[52:53], v[52:53], v[206:207] op_sel_hi:[1,0]
	v_pk_mul_f32 v[50:51], v[50:51], v[206:207] op_sel_hi:[1,0]
	v_pk_mul_f32 v[48:49], v[48:49], v[206:207] op_sel_hi:[1,0]
	v_pk_mul_f32 v[46:47], v[46:47], v[206:207] op_sel_hi:[1,0]
	v_pk_mul_f32 v[44:45], v[44:45], v[206:207] op_sel_hi:[1,0]
	v_pk_mul_f32 v[42:43], v[42:43], v[206:207] op_sel_hi:[1,0]
	v_pk_mul_f32 v[40:41], v[40:41], v[206:207] op_sel_hi:[1,0]
	v_pk_mul_f32 v[38:39], v[38:39], v[206:207] op_sel_hi:[1,0]
	v_pk_mul_f32 v[36:37], v[36:37], v[206:207] op_sel_hi:[1,0]
	v_pk_mul_f32 v[34:35], v[34:35], v[206:207] op_sel_hi:[1,0]
	v_pk_mul_f32 v[32:33], v[32:33], v[206:207] op_sel_hi:[1,0]
	v_pk_mul_f32 v[30:31], v[30:31], v[206:207] op_sel_hi:[1,0]
	v_pk_mul_f32 v[28:29], v[28:29], v[206:207] op_sel_hi:[1,0]
	v_pk_mul_f32 v[26:27], v[26:27], v[206:207] op_sel_hi:[1,0]
	v_pk_mul_f32 v[24:25], v[24:25], v[206:207] op_sel_hi:[1,0]
	v_pk_mul_f32 v[22:23], v[22:23], v[206:207] op_sel_hi:[1,0]
	v_pk_mul_f32 v[20:21], v[20:21], v[206:207] op_sel_hi:[1,0]
	v_pk_mul_f32 v[18:19], v[18:19], v[206:207] op_sel_hi:[1,0]
	v_pk_mul_f32 v[16:17], v[16:17], v[206:207] op_sel_hi:[1,0]
	s_mov_b32 s60, 0

; #define DF_DMA(t, bufi) do { const bf16_t* sb_ = sbase + (size_t)(64 * (t)) * QKVW; const unsigned base_ = (unsigned)__builtin_amdgcn_readfirstlane(ldsb + (bufi) * DF_STAGE); \
;         glds16s(sb_, oK, base_ + dK); glds16s(sb_, oK + 128u, base_ + DF_K2 + dK); glds16s(sb_, oV0, base_ + dV0); glds16s(sb_, oV1, base_ + dV1); } while (0)
; #define DF_WAITBAR(N) asm volatile("s_waitcnt vmcnt(" #N ") lgkmcnt(0)\n\ts_barrier" ::: "memory")
; DI void diff_unit(const Args& A, const bf16_t* QKV, bf16_t* ATT, unsigned char* lds, LAS unsigned char* lds3, int b, int head, int qb, int tid, int wid, int lane) {
;     ...
;     for (int t = 0; t < nst; ++t) {
;         { const int tl = (t + 2 < nst) ? t + 2 : nst - 1; DF_DMA(tl, (t + 2) & 3); }
;         diff_stage(lds, lds3, t & 3, t, comp, q0, r32, hi, vlane, skew, qf, o, m, l, pp, pvo, have_prev);
;         DF_WAITBAR(4);
;     }
.Ldf2b_bar:
	s_waitcnt vmcnt(4) lgkmcnt(0)
	s_add_i32 s26, s26, 0x8000
	s_and_b32 s66, s26, 0x18000
	v_add_u32_e32 v2, s66, v160
	v_add_u32_e32 v3, v2, v161
	v_add_u32_e32 v4, v2, v162
	v_add_u32_e32 v5, v2, v163
	v_add_u32_e32 v2, v2, v164
	s_add_i32 s50, s26, 0x18000
	s_cmp_eq_u32 s61, 0
	s_cselect_b32 s50, s26, s50
	s_and_b32 s50, s50, 0x18000
	v_add_u32_e32 v6, s50, v165
	s_add_i32 s27, s27, 64
	v_subrev_u32_e32 v183, 64, v183
	s_add_i32 s31, s30, 1
	s_add_i32 s66, s31, 2
	s_cmp_lt_u32 s31, s11
	s_cselect_b32 s64, s66, s29
	s_lshl_b32 s65, s64, 6
	s_mul_i32 s64, s64, 0x60000
	s_mul_hi_u32 s65, s65, 0x1800
	s_add_u32 s64, s24, s64
	s_addc_u32 s65, s25, s65
	s_lshl_b32 s66, s66, 15
	s_and_b32 s66, s66, 0x18000
	s_add_i32 s67, s66, s22
	s_add_i32 s68, s66, s28
	s_add_i32 s69, s66, s36
	s_add_i32 s70, s66, s37
	s_cmp_eq_u32 s30, s29
	s_barrier
	s_cbranch_scc1 .Ldf2b_exit
	s_mov_b32 s30, s31
	s_branch .Ldf2b_loop

; DI f32x16 mfma32(bf16x8 a, bf16x8 b, f32x16 c) { return __builtin_amdgcn_mfma_f32_32x32x16_bf16(a, b, c, 0, 0, 0); }
; #define DF_VLD(VF, VOFF, H) do { _Pragma("unroll") for (int d2 = 0; d2 < 2; ++d2) { LAS unsigned char* vb_ = lds3 + (VOFF) + (2 * (H) + d2) * 4096; VF[2 * d2] = vfrag(vb_); VF[2 * d2 + 1] = vfrag(vb_ + 1024); } } while (0)
; #define DF_PVM(VF, P0, P1, H) do { _Pragma("unroll") for (int d2 = 0; d2 < 2; ++d2) { o[2 * (H) + d2] = mfma32(VF[2 * d2], P0, o[2 * (H) + d2]); o[2 * (H) + d2] = mfma32(VF[2 * d2 + 1], P1, o[2 * (H) + d2]); } } while (0)
; DI void diff_stage(const unsigned char* lds, LAS unsigned char* lds3, int buf, int t, int comp, int q0, int r32, int hi, int vlane, bool skew,
;                    const bf16x8 (&qf)[4], f32x16 (&o)[4], float& m, float& l, bf16x8 (&pp)[4], int& pvo, bool& have_prev) {
;     const int k0 = 64 * t;
;     if (k0 > q0 + 31) return;
;     const unsigned char* sb = lds + buf * DF_STAGE + comp * DF_K2 + r32 * 128; const int ke16 = (hi ^ ((r32 >> 1) & 7)) * 16;
;     bf16x8 vf[4];
;     if (skew && have_prev) {
; #pragma unroll
;         for (int sub = 0; sub < 2; ++sub) { DF_VLD(vf, pvo + sub * 2048, 0); DF_PVM(vf, pp[2 * sub], pp[2 * sub + 1], 0); DF_VLD(vf, pvo + sub * 2048, 1); DF_PVM(vf, pp[2 * sub], pp[2 * sub + 1], 1); }
;     }
;     f32x16 s0, s1;
; #pragma unroll
;     for (int i = 0; i < 16; ++i) { s0[i] = 0.f; s1[i] = 0.f; }
;     {
;         bf16x8 k0f[4], k1f[4];
; #pragma unroll
;         for (int c = 0; c < 4; ++c) { k0f[c] = *(const bf16x8*)(sb + ((32 * c) ^ ke16)); k1f[c] = *(const bf16x8*)(sb + 32 * 128 + ((32 * c) ^ ke16)); }
; #pragma unroll
;         for (int c = 0; c < 4; ++c) { s0 = mfma32(k0f[c], qf[c], s0); s1 = mfma32(k1f[c], qf[c], s1); }
;     }
;     if (k0 + 63 > q0) {
;         const int dq = q0 + r32 - k0 - 4 * hi;
; #pragma unroll
;         for (int i = 0; i < 16; ++i) { const int ci = (i & 3) + 8 * (i >> 2); s0[i] = (ci > dq) ? -INFINITY : s0[i]; s1[i] = (ci + 32 > dq) ? -INFINITY : s1[i]; }
;     }
.Ldf2a_loop:
	s_sub_i32 s71, s27, 63
	s_cmp_gt_u32 s71, s49
	s_cbranch_scc1 .Ldf2a_skip
	s_and_b32 s31, s26, 0x18000
	ds_read_b128 v[208:211], v3
	ds_read_b128 v[212:215], v3 offset:4096
	ds_read_b128 v[216:219], v4
	ds_read_b128 v[220:223], v4 offset:4096
	ds_read_b128 v[224:227], v5
	ds_read_b128 v[228:231], v5 offset:4096
	ds_read_b128 v[232:235], v2
	ds_read_b128 v[236:239], v2 offset:4096
	s_mov_b32 m0, s67
	s_nop 0
	global_load_lds_dwordx4 v156, s[64:65]
	s_mov_b32 m0, s68
	s_nop 0
	global_load_lds_dwordx4 v159, s[64:65]
	s_mov_b32 m0, s69
	s_nop 0
	global_load_lds_dwordx4 v157, s[64:65]
	s_mov_b32 m0, s70
	s_nop 0
	global_load_lds_dwordx4 v158, s[64:65]
	s_waitcnt lgkmcnt(7)
	v_mfma_f32_32x32x16_bf16 v[96:111], v[208:211], v[124:127], 0
	s_waitcnt lgkmcnt(6)
	v_mfma_f32_32x32x16_bf16 v[80:95], v[212:215], v[124:127], 0
	s_waitcnt lgkmcnt(5)
	v_mfma_f32_32x32x16_bf16 v[96:111], v[216:219], v[120:123], v[96:111]
	s_waitcnt lgkmcnt(4)
	v_mfma_f32_32x32x16_bf16 v[80:95], v[220:223], v[120:123], v[80:95]
	s_waitcnt lgkmcnt(3)
	v_mfma_f32_32x32x16_bf16 v[96:111], v[224:227], v[116:119], v[96:111]
	s_waitcnt lgkmcnt(2)
	v_mfma_f32_32x32x16_bf16 v[80:95], v[228:231], v[116:119], v[80:95]
	s_waitcnt lgkmcnt(1)
	v_mfma_f32_32x32x16_bf16 v[96:111], v[232:235], v[112:115], v[96:111]
	s_waitcnt lgkmcnt(0)
	v_mfma_f32_32x32x16_bf16 v[80:95], v[236:239], v[112:115], v[80:95]
	ds_read_b64_tr_b16 v[208:209], v6 offset:16384
	ds_read_b64_tr_b16 v[210:211], v6 offset:16896
	ds_read_b64_tr_b16 v[212:213], v6 offset:17408
	ds_read_b64_tr_b16 v[214:215], v6 offset:17920
	ds_read_b64_tr_b16 v[216:217], v6 offset:20480
	ds_read_b64_tr_b16 v[218:219], v6 offset:20992
	ds_read_b64_tr_b16 v[220:221], v6 offset:21504
	ds_read_b64_tr_b16 v[222:223], v6 offset:22016
	ds_read_b64_tr_b16 v[224:225], v6 offset:24576
	ds_read_b64_tr_b16 v[226:227], v6 offset:25088
	ds_read_b64_tr_b16 v[228:229], v6 offset:25600
	ds_read_b64_tr_b16 v[230:231], v6 offset:26112
	s_cmp_le_u32 s27, s10
	s_cbranch_scc1 .Ldf2a_nodiag
	s_nop 7
	v_cmp_lt_i32_e32 vcc, -1, v183
	s_nop 1
	v_cndmask_b32_e32 v96, v176, v96, vcc
	v_cmp_lt_i32_e32 vcc, 31, v183
	s_nop 1
	v_cndmask_b32_e32 v80, v176, v80, vcc
	v_cmp_lt_i32_e32 vcc, 0, v183
	s_nop 1
	v_cndmask_b32_e32 v97, v176, v97, vcc
	v_cmp_lt_i32_e32 vcc, 32, v183
	s_nop 1
	v_cndmask_b32_e32 v81, v176, v81, vcc
	v_cmp_lt_i32_e32 vcc, 1, v183
	s_nop 1
	v_cndmask_b32_e32 v98, v176, v98, vcc
	v_cmp_lt_i32_e32 vcc, 33, v183
	s_nop 1
	v_cndmask_b32_e32 v82, v176, v82, vcc
	v_cmp_lt_i32_e32 vcc, 2, v183
	s_nop 1
	v_cndmask_b32_e32 v99, v176, v99, vcc
	v_cmp_lt_i32_e32 vcc, 34, v183
	s_nop 1
	v_cndmask_b32_e32 v83, v176, v83, vcc
	v_cmp_lt_i32_e32 vcc, 7, v183
	s_nop 1
	v_cndmask_b32_e32 v100, v176, v100, vcc
	v_cmp_lt_i32_e32 vcc, 39, v183
	s_nop 1
	v_cndmask_b32_e32 v84, v176, v84, vcc
	v_cmp_lt_i32_e32 vcc, 8, v183
	s_nop 1
	v_cndmask_b32_e32 v101, v176, v101, vcc
	v_cmp_lt_i32_e32 vcc, 40, v183
	s_nop 1
	v_cndmask_b32_e32 v85, v176, v85, vcc
	v_cmp_lt_i32_e32 vcc, 9, v183
	s_nop 1
	v_cndmask_b32_e32 v102, v176, v102, vcc
	v_cmp_lt_i32_e32 vcc, 41, v183
	s_nop 1
	v_cndmask_b32_e32 v86, v176, v86, vcc
	v_cmp_lt_i32_e32 vcc, 10, v183
	s_nop 1
	v_cndmask_b32_e32 v103, v176, v103, vcc
	v_cmp_lt_i32_e32 vcc, 42, v183
	s_nop 1
	v_cndmask_b32_e32 v87, v176, v87, vcc
	v_cmp_lt_i32_e32 vcc, 15, v183
	s_nop 1
	v_cndmask_b32_e32 v104, v176, v104, vcc
	v_cmp_lt_i32_e32 vcc, 47, v183
	s_nop 1
	v_cndmask_b32_e32 v88, v176, v88, vcc
	v_cmp_lt_i32_e32 vcc, 16, v183
	s_nop 1
	v_cndmask_b32_e32 v105, v176, v105, vcc
	v_cmp_lt_i32_e32 vcc, 48, v183
	s_nop 1
	v_cndmask_b32_e32 v89, v176, v89, vcc
	v_cmp_lt_i32_e32 vcc, 17, v183
	s_nop 1
	v_cndmask_b32_e32 v106, v176, v106, vcc
	v_cmp_lt_i32_e32 vcc, 49, v183
	s_nop 1
	v_cndmask_b32_e32 v90, v176, v90, vcc
	v_cmp_lt_i32_e32 vcc, 18, v183
	s_nop 1
	v_cndmask_b32_e32 v107, v176, v107, vcc
	v_cmp_lt_i32_e32 vcc, 50, v183
	s_nop 1
	v_cndmask_b32_e32 v91, v176, v91, vcc
	v_cmp_lt_i32_e32 vcc, 23, v183
	s_nop 1
	v_cndmask_b32_e32 v108, v176, v108, vcc
	v_cmp_lt_i32_e32 vcc, 55, v183
	s_nop 1
	v_cndmask_b32_e32 v92, v176, v92, vcc
	v_cmp_lt_i32_e32 vcc, 24, v183
	s_nop 1
	v_cndmask_b32_e32 v109, v176, v109, vcc
	v_cmp_lt_i32_e32 vcc, 56, v183
	s_nop 1
	v_cndmask_b32_e32 v93, v176, v93, vcc
	v_cmp_lt_i32_e32 vcc, 25, v183
	s_nop 1
	v_cndmask_b32_e32 v110, v176, v110, vcc
	v_cmp_lt_i32_e32 vcc, 57, v183
	s_nop 1
	v_cndmask_b32_e32 v94, v176, v94, vcc
	v_cmp_lt_i32_e32 vcc, 26, v183
	s_nop 1
	v_cndmask_b32_e32 v111, v176, v111, vcc
	v_cmp_lt_i32_e32 vcc, 58, v183
	s_nop 1
	v_cndmask_b32_e32 v95, v176, v95, vcc

; #define DF_DMA(t, bufi) do { const bf16_t* sb_ = sbase + (size_t)(64 * (t)) * QKVW; const unsigned base_ = (unsigned)__builtin_amdgcn_readfirstlane(ldsb + (bufi) * DF_STAGE); \
;         glds16s(sb_, oK, base_ + dK); glds16s(sb_, oK + 128u, base_ + DF_K2 + dK); glds16s(sb_, oV0, base_ + dV0); glds16s(sb_, oV1, base_ + dV1); } while (0)
; #define DF_WAITBAR(N) asm volatile("s_waitcnt vmcnt(" #N ") lgkmcnt(0)\n\ts_barrier" ::: "memory")
; DI void diff_unit(const Args& A, const bf16_t* QKV, bf16_t* ATT, unsigned char* lds, LAS unsigned char* lds3, int b, int head, int qb, int tid, int wid, int lane) {
;     ...
;     for (int t = 0; t < nst; ++t) {
;         { const int tl = (t + 2 < nst) ? t + 2 : nst - 1; DF_DMA(tl, (t + 2) & 3); }
;         diff_stage(lds, lds3, t & 3, t, comp, q0, r32, hi, vlane, skew, qf, o, m, l, pp, pvo, have_prev);
;         DF_WAITBAR(4);
;     }
.Ldf2a_bar:
	s_waitcnt vmcnt(4) lgkmcnt(0)
	s_add_i32 s26, s26, 0x8000
	s_and_b32 s66, s26, 0x18000
	v_add_u32_e32 v2, s66, v160
	v_add_u32_e32 v3, v2, v161
	v_add_u32_e32 v4, v2, v162
	v_add_u32_e32 v5, v2, v163
	v_add_u32_e32 v2, v2, v164
	v_add_u32_e32 v6, s66, v165
	s_add_i32 s27, s27, 64
	v_subrev_u32_e32 v183, 64, v183
	s_add_i32 s31, s30, 1
	s_add_i32 s66, s31, 2
	s_cmp_lt_u32 s31, s11
	s_cselect_b32 s64, s66, s29
	s_lshl_b32 s65, s64, 6
	s_mul_i32 s64, s64, 0x60000
	s_mul_hi_u32 s65, s65, 0x1800
	s_add_u32 s64, s24, s64
	s_addc_u32 s65, s25, s65
	s_lshl_b32 s66, s66, 15
	s_and_b32 s66, s66, 0x18000
	s_add_i32 s67, s66, s22
	s_add_i32 s68, s66, s28
	s_add_i32 s69, s66, s36
	s_add_i32 s70, s66, s37
	s_cmp_eq_u32 s30, s29
	s_barrier
	s_cbranch_scc1 .Ldf2a_exit
	s_mov_b32 s30, s31
	s_branch .Ldf2a_loop
